# grid barrier: non-leader workgroups poll the global generation word directly instead of waiting for their XCD leader's relay
# speedup vs baseline: 1.0057x; 1.0057x over previous
.LBB0_112:
	s_or_b64 exec, exec, s[10:11]
	v_cvt_f32_u32_e32 v4, v2
	s_waitcnt vmcnt(0)
	v_readfirstlane_b32 s3, v3
	v_sub_u32_e32 v3, 0, v2
	v_rcp_iflag_f32_e32 v4, v4
	v_add_u32_e32 v5, s3, v1
	v_mul_f32_e32 v4, 0x4f7ffffe, v4
	v_cvt_u32_f32_e32 v4, v4
	v_mul_lo_u32 v1, v3, v4
	v_mul_hi_u32 v1, v4, v1
	v_add_u32_e32 v1, v4, v1
	v_mul_hi_u32 v1, v5, v1
	v_mul_lo_u32 v3, v1, v2
	v_sub_u32_e32 v3, v5, v3
	v_add_u32_e32 v4, 1, v1
	v_cmp_ge_u32_e32 vcc, v3, v2
	s_nop 1
	v_cndmask_b32_e32 v1, v1, v4, vcc
	v_sub_u32_e32 v4, v3, v2
	v_cndmask_b32_e32 v3, v3, v4, vcc
	v_add_u32_e32 v4, 1, v1
	v_cmp_ge_u32_e32 vcc, v3, v2
	v_add_u32_e32 v3, 1, v5
	s_nop 0
	v_cndmask_b32_e32 v1, v1, v4, vcc
	v_mul_lo_u32 v4, v2, v1
	v_add_u32_e32 v2, v4, v2
	v_cmp_ne_u32_e32 vcc, v3, v2
	s_and_saveexec_b64 s[8:9], vcc
	s_xor_b64 s[8:9], exec, s[8:9]
	s_cbranch_execz .LBB0_126
	s_waitcnt lgkmcnt(0)
	v_mov_b32_e32 v0, 0x3500
	global_load_dword v0, v0, s[48:49] sc1
	s_add_u32 s12, s48, 0x3500
	s_addc_u32 s13, s49, 0
	s_waitcnt vmcnt(0)
	v_cmp_eq_u32_e32 vcc, v0, v1
	s_and_saveexec_b64 s[10:11], vcc
	s_cbranch_execz .LBB0_125
	s_mov_b32 s3, 1
	s_mov_b64 s[14:15], 0
	v_mov_b32_e32 v0, 0
	s_branch .LBB0_116

.LBB0_1477:
	s_or_b64 exec, exec, s[6:7]
	v_cvt_f32_u32_e32 v4, v2
	s_waitcnt vmcnt(0)
	v_readfirstlane_b32 s4, v3
	v_sub_u32_e32 v3, 0, v2
	v_rcp_iflag_f32_e32 v4, v4
	v_add_u32_e32 v5, s4, v1
	v_mul_f32_e32 v4, 0x4f7ffffe, v4
	v_cvt_u32_f32_e32 v4, v4
	v_mul_lo_u32 v1, v3, v4
	v_mul_hi_u32 v1, v4, v1
	v_add_u32_e32 v1, v4, v1
	v_mul_hi_u32 v1, v5, v1
	v_mul_lo_u32 v3, v1, v2
	v_sub_u32_e32 v3, v5, v3
	v_add_u32_e32 v4, 1, v1
	v_cmp_ge_u32_e32 vcc, v3, v2
	s_nop 1
	v_cndmask_b32_e32 v1, v1, v4, vcc
	v_sub_u32_e32 v4, v3, v2
	v_cndmask_b32_e32 v3, v3, v4, vcc
	v_add_u32_e32 v4, 1, v1
	v_cmp_ge_u32_e32 vcc, v3, v2
	v_add_u32_e32 v3, 1, v5
	s_nop 0
	v_cndmask_b32_e32 v1, v1, v4, vcc
	v_mul_lo_u32 v4, v2, v1
	v_add_u32_e32 v2, v4, v2
	v_cmp_ne_u32_e32 vcc, v3, v2
	s_and_saveexec_b64 s[4:5], vcc
	s_xor_b64 s[4:5], exec, s[4:5]
	s_cbranch_execz .LBB0_1491
	s_waitcnt lgkmcnt(0)
	v_mov_b32_e32 v0, 0x3500
	global_load_dword v0, v0, s[48:49] sc1
	s_add_u32 s8, s48, 0x3500
	s_addc_u32 s9, s49, 0
	s_waitcnt vmcnt(0)
	v_cmp_eq_u32_e32 vcc, v0, v1
	s_and_saveexec_b64 s[6:7], vcc
	s_cbranch_execz .LBB0_1490
	s_mov_b32 s20, 1
	s_mov_b64 s[10:11], 0
	v_mov_b32_e32 v0, 0
	s_branch .LBB0_1481
